# GEMM K-loops: removed the mid-segment s_setprio 0/1 pair and the redundant post-barrier lgkmcnt(0) (32 back-to-back MFMAs per segment)
# speedup vs baseline: 1.0175x; 1.0175x over previous
.LBB0_264:
	s_or_b32 s22, s56, 1
	s_lshl_b64 s[2:3], s[22:23], 7
	s_add_u32 s58, s76, s2
	s_addc_u32 s68, s77, s3
	s_add_i32 s22, s56, 2
	s_lshl_b64 s[38:39], s[22:23], 7
	s_add_u32 s69, s76, s38
	s_addc_u32 s72, s77, s39
	s_and_b64 s[2:3], s[28:29], exec
	s_cselect_b32 s3, s72, s11
	s_cselect_b32 s2, s69, s45
	s_add_u32 s38, s26, s38
	s_addc_u32 s39, s27, s39
	s_and_b64 s[28:29], s[28:29], exec
	s_cselect_b32 s29, s39, s31
	s_cselect_b32 s28, s38, s54
	s_add_i32 s69, 0, 0x10000
	s_add_i32 s72, 0, 0x14000
	v_add_u32_e32 v152, s69, v160
	v_add_u32_e32 v156, s72, v160
	ds_read_b128 v[140:143], v152
	ds_read_b128 v[144:147], v152 offset:1024
	ds_read_b128 v[148:151], v152 offset:2048
	ds_read_b128 v[152:155], v152 offset:3072
	ds_read_b128 v[168:171], v156
	ds_read_b128 v[172:175], v156 offset:1024
	ds_read_b128 v[176:179], v156 offset:2048
	ds_read_b128 v[180:183], v156 offset:3072
	s_add_u32 s38, s58, 0x80000
	s_addc_u32 s39, s68, 0
	v_lshl_add_u64 v[156:157], s[38:39], 0, v[130:131]
	s_add_i32 m0, s93, 0xc000
	ds_read_b128 v[184:187], v166
	ds_read_b128 v[188:191], v166 offset:1024
	ds_read_b128 v[192:195], v166 offset:2048
	ds_read_b128 v[196:199], v166 offset:3072
	ds_read_b128 v[226:229], v166 offset:4096
	ds_read_b128 v[230:233], v166 offset:5120
	ds_read_b128 v[234:237], v166 offset:6144
	ds_read_b128 v[238:241], v166 offset:7168
	global_load_lds_dwordx4 v[156:157], off
	v_lshl_add_u64 v[156:157], s[38:39], 0, v[134:135]
	s_add_i32 m0, s93, 0xe000
	s_nop 0
	global_load_lds_dwordx4 v[156:157], off
	s_waitcnt vmcnt(8)
	s_waitcnt lgkmcnt(0)
	s_barrier
	s_setprio 1
	v_mfma_f32_16x16x32_bf16 v[126:129], v[140:143], v[184:187], v[126:129]
	v_mfma_f32_16x16x32_bf16 v[122:125], v[148:151], v[184:187], v[122:125]
	v_mfma_f32_16x16x32_bf16 v[110:113], v[140:143], v[192:195], v[110:113]
	v_mfma_f32_16x16x32_bf16 v[106:109], v[148:151], v[192:195], v[106:109]
	v_mfma_f32_16x16x32_bf16 v[94:97], v[140:143], v[226:229], v[94:97]
	v_mfma_f32_16x16x32_bf16 v[90:93], v[148:151], v[226:229], v[90:93]
	v_mfma_f32_16x16x32_bf16 v[78:81], v[140:143], v[234:237], v[78:81]
	v_mfma_f32_16x16x32_bf16 v[74:77], v[148:151], v[234:237], v[74:77]
	v_mfma_f32_16x16x32_bf16 v[126:129], v[144:147], v[188:191], v[126:129]
	v_mfma_f32_16x16x32_bf16 v[122:125], v[152:155], v[188:191], v[122:125]
	v_mfma_f32_16x16x32_bf16 v[110:113], v[144:147], v[196:199], v[110:113]
	v_mfma_f32_16x16x32_bf16 v[106:109], v[152:155], v[196:199], v[106:109]
	v_mfma_f32_16x16x32_bf16 v[94:97], v[144:147], v[230:233], v[94:97]
	v_mfma_f32_16x16x32_bf16 v[90:93], v[152:155], v[230:233], v[90:93]
	v_mfma_f32_16x16x32_bf16 v[78:81], v[144:147], v[238:241], v[78:81]
	v_mfma_f32_16x16x32_bf16 v[74:77], v[152:155], v[238:241], v[74:77]
	v_mfma_f32_16x16x32_bf16 v[118:121], v[168:171], v[184:187], v[118:121]
	v_mfma_f32_16x16x32_bf16 v[114:117], v[176:179], v[184:187], v[114:117]
	v_mfma_f32_16x16x32_bf16 v[102:105], v[168:171], v[192:195], v[102:105]
	v_mfma_f32_16x16x32_bf16 v[98:101], v[176:179], v[192:195], v[98:101]
	v_mfma_f32_16x16x32_bf16 v[86:89], v[168:171], v[226:229], v[86:89]
	v_mfma_f32_16x16x32_bf16 v[82:85], v[176:179], v[226:229], v[82:85]
	v_mfma_f32_16x16x32_bf16 v[70:73], v[168:171], v[234:237], v[70:73]
	v_mfma_f32_16x16x32_bf16 v[66:69], v[176:179], v[234:237], v[66:69]
	v_mfma_f32_16x16x32_bf16 v[118:121], v[172:175], v[188:191], v[118:121]
	v_mfma_f32_16x16x32_bf16 v[114:117], v[180:183], v[188:191], v[114:117]
	v_mfma_f32_16x16x32_bf16 v[102:105], v[172:175], v[196:199], v[102:105]
	v_mfma_f32_16x16x32_bf16 v[98:101], v[180:183], v[196:199], v[98:101]
	v_mfma_f32_16x16x32_bf16 v[86:89], v[172:175], v[230:233], v[86:89]
	v_mfma_f32_16x16x32_bf16 v[82:85], v[180:183], v[230:233], v[82:85]
	v_mfma_f32_16x16x32_bf16 v[70:73], v[172:175], v[238:241], v[70:73]
	v_mfma_f32_16x16x32_bf16 v[66:69], v[180:183], v[238:241], v[66:69]
	s_setprio 0
	s_barrier
	s_add_i32 s38, s69, s21
	v_lshl_add_u64 v[156:157], s[28:29], 0, v[132:133]
	s_mov_b32 m0, s38
	ds_read_b128 v[184:187], v166 offset:16384
	ds_read_b128 v[188:191], v166 offset:17408
	ds_read_b128 v[192:195], v166 offset:18432
	ds_read_b128 v[196:199], v166 offset:19456
	ds_read_b128 v[226:229], v166 offset:20480
	ds_read_b128 v[230:233], v166 offset:21504
	ds_read_b128 v[234:237], v166 offset:22528
	ds_read_b128 v[238:241], v166 offset:23552
	global_load_lds_dwordx4 v[156:157], off
	s_add_i32 m0, s38, 0x2000
	s_add_u32 s38, s28, 0x80000
	v_lshl_add_u64 v[200:201], s[28:29], 0, v[136:137]
	s_addc_u32 s39, s29, 0
	s_add_i32 s58, s72, s21
	global_load_lds_dwordx4 v[200:201], off
	v_lshl_add_u64 v[206:207], s[38:39], 0, v[132:133]
	s_mov_b32 m0, s58
	v_lshl_add_u64 v[242:243], s[2:3], 0, v[134:135]
	global_load_lds_dwordx4 v[206:207], off
	v_lshl_add_u64 v[206:207], s[38:39], 0, v[136:137]
	s_add_i32 m0, s58, 0x2000
	s_nop 0
	global_load_lds_dwordx4 v[206:207], off
	v_lshl_add_u64 v[206:207], s[2:3], 0, v[130:131]
	s_mov_b32 m0, s93
	s_nop 0
	global_load_lds_dwordx4 v[206:207], off
	s_mov_b32 m0, s12
	s_nop 0
	global_load_lds_dwordx4 v[242:243], off
	s_waitcnt vmcnt(8)
	s_waitcnt lgkmcnt(0)
	s_barrier
	s_setprio 1
	v_mfma_f32_16x16x32_bf16 v[62:65], v[140:143], v[184:187], v[62:65]
	v_mfma_f32_16x16x32_bf16 v[58:61], v[148:151], v[184:187], v[58:61]
	v_mfma_f32_16x16x32_bf16 v[46:49], v[140:143], v[192:195], v[46:49]
	v_mfma_f32_16x16x32_bf16 v[42:45], v[148:151], v[192:195], v[42:45]
	v_mfma_f32_16x16x32_bf16 v[30:33], v[140:143], v[226:229], v[30:33]
	v_mfma_f32_16x16x32_bf16 v[26:29], v[148:151], v[226:229], v[26:29]
	v_mfma_f32_16x16x32_bf16 v[14:17], v[140:143], v[234:237], v[14:17]
	v_mfma_f32_16x16x32_bf16 v[10:13], v[148:151], v[234:237], v[10:13]
	v_mfma_f32_16x16x32_bf16 v[62:65], v[144:147], v[188:191], v[62:65]
	v_mfma_f32_16x16x32_bf16 v[58:61], v[152:155], v[188:191], v[58:61]
	v_mfma_f32_16x16x32_bf16 v[46:49], v[144:147], v[196:199], v[46:49]
	v_mfma_f32_16x16x32_bf16 v[42:45], v[152:155], v[196:199], v[42:45]
	v_mfma_f32_16x16x32_bf16 v[30:33], v[144:147], v[230:233], v[30:33]
	v_mfma_f32_16x16x32_bf16 v[26:29], v[152:155], v[230:233], v[26:29]
	v_mfma_f32_16x16x32_bf16 v[14:17], v[144:147], v[238:241], v[14:17]
	v_mfma_f32_16x16x32_bf16 v[10:13], v[152:155], v[238:241], v[10:13]
	v_mfma_f32_16x16x32_bf16 v[54:57], v[168:171], v[184:187], v[54:57]
	v_mfma_f32_16x16x32_bf16 v[50:53], v[176:179], v[184:187], v[50:53]
	v_mfma_f32_16x16x32_bf16 v[38:41], v[168:171], v[192:195], v[38:41]
	v_mfma_f32_16x16x32_bf16 v[34:37], v[176:179], v[192:195], v[34:37]
	v_mfma_f32_16x16x32_bf16 v[22:25], v[168:171], v[226:229], v[22:25]
	v_mfma_f32_16x16x32_bf16 v[18:21], v[176:179], v[226:229], v[18:21]
	v_mfma_f32_16x16x32_bf16 v[6:9], v[168:171], v[234:237], v[6:9]
	v_mfma_f32_16x16x32_bf16 v[2:5], v[176:179], v[234:237], v[2:5]
	v_mfma_f32_16x16x32_bf16 v[54:57], v[172:175], v[188:191], v[54:57]
	v_mfma_f32_16x16x32_bf16 v[50:53], v[180:183], v[188:191], v[50:53]
	v_mfma_f32_16x16x32_bf16 v[38:41], v[172:175], v[196:199], v[38:41]
	v_mfma_f32_16x16x32_bf16 v[34:37], v[180:183], v[196:199], v[34:37]
	v_mfma_f32_16x16x32_bf16 v[22:25], v[172:175], v[230:233], v[22:25]
	v_mfma_f32_16x16x32_bf16 v[18:21], v[180:183], v[230:233], v[18:21]
	v_mfma_f32_16x16x32_bf16 v[6:9], v[172:175], v[238:241], v[6:9]
	v_mfma_f32_16x16x32_bf16 v[2:5], v[180:183], v[238:241], v[2:5]
	s_setprio 0
	s_barrier
	s_add_i32 s38, 0, 0x18000
	s_add_i32 s39, 0, 0x1c000
	v_add_u32_e32 v152, s38, v160
	v_add_u32_e32 v167, s39, v160
	ds_read_b128 v[140:143], v152
	ds_read_b128 v[144:147], v152 offset:1024
	ds_read_b128 v[148:151], v152 offset:2048
	ds_read_b128 v[152:155], v152 offset:3072
	ds_read_b128 v[168:171], v167
	ds_read_b128 v[172:175], v167 offset:1024
	ds_read_b128 v[176:179], v167 offset:2048
	ds_read_b128 v[180:183], v167 offset:3072
	s_add_u32 s2, s2, 0x80000
	s_addc_u32 s3, s3, 0
	s_mov_b32 m0, s51
	v_lshl_add_u64 v[244:245], s[2:3], 0, v[130:131]
	ds_read_b128 v[184:187], v166 offset:32768
	ds_read_b128 v[188:191], v166 offset:33792
	ds_read_b128 v[192:195], v166 offset:34816
	ds_read_b128 v[196:199], v166 offset:35840
	ds_read_b128 v[226:229], v166 offset:36864
	ds_read_b128 v[230:233], v166 offset:37888
	ds_read_b128 v[234:237], v166 offset:38912
	ds_read_b128 v[238:241], v166 offset:39936
	global_load_lds_dwordx4 v[244:245], off
	v_lshl_add_u64 v[244:245], s[2:3], 0, v[134:135]
	s_mov_b32 m0, s14
	s_nop 0
	global_load_lds_dwordx4 v[244:245], off
	s_waitcnt vmcnt(8)
	s_waitcnt lgkmcnt(0)
	s_barrier
	s_setprio 1
	v_mfma_f32_16x16x32_bf16 v[126:129], v[140:143], v[184:187], v[126:129]
	v_mfma_f32_16x16x32_bf16 v[122:125], v[148:151], v[184:187], v[122:125]
	v_mfma_f32_16x16x32_bf16 v[110:113], v[140:143], v[192:195], v[110:113]
	v_mfma_f32_16x16x32_bf16 v[106:109], v[148:151], v[192:195], v[106:109]
	v_mfma_f32_16x16x32_bf16 v[94:97], v[140:143], v[226:229], v[94:97]
	v_mfma_f32_16x16x32_bf16 v[90:93], v[148:151], v[226:229], v[90:93]
	v_mfma_f32_16x16x32_bf16 v[78:81], v[140:143], v[234:237], v[78:81]
	v_mfma_f32_16x16x32_bf16 v[74:77], v[148:151], v[234:237], v[74:77]
	v_mfma_f32_16x16x32_bf16 v[126:129], v[144:147], v[188:191], v[126:129]
	v_mfma_f32_16x16x32_bf16 v[122:125], v[152:155], v[188:191], v[122:125]
	v_mfma_f32_16x16x32_bf16 v[110:113], v[144:147], v[196:199], v[110:113]
	v_mfma_f32_16x16x32_bf16 v[106:109], v[152:155], v[196:199], v[106:109]
	v_mfma_f32_16x16x32_bf16 v[94:97], v[144:147], v[230:233], v[94:97]
	v_mfma_f32_16x16x32_bf16 v[90:93], v[152:155], v[230:233], v[90:93]
	v_mfma_f32_16x16x32_bf16 v[78:81], v[144:147], v[238:241], v[78:81]
	v_mfma_f32_16x16x32_bf16 v[74:77], v[152:155], v[238:241], v[74:77]
	v_mfma_f32_16x16x32_bf16 v[118:121], v[168:171], v[184:187], v[118:121]
	v_mfma_f32_16x16x32_bf16 v[114:117], v[176:179], v[184:187], v[114:117]
	v_mfma_f32_16x16x32_bf16 v[102:105], v[168:171], v[192:195], v[102:105]
	v_mfma_f32_16x16x32_bf16 v[98:101], v[176:179], v[192:195], v[98:101]
	v_mfma_f32_16x16x32_bf16 v[86:89], v[168:171], v[226:229], v[86:89]
	v_mfma_f32_16x16x32_bf16 v[82:85], v[176:179], v[226:229], v[82:85]
	v_mfma_f32_16x16x32_bf16 v[70:73], v[168:171], v[234:237], v[70:73]
	v_mfma_f32_16x16x32_bf16 v[66:69], v[176:179], v[234:237], v[66:69]
	v_mfma_f32_16x16x32_bf16 v[118:121], v[172:175], v[188:191], v[118:121]
	v_mfma_f32_16x16x32_bf16 v[114:117], v[180:183], v[188:191], v[114:117]
	v_mfma_f32_16x16x32_bf16 v[102:105], v[172:175], v[196:199], v[102:105]
	v_mfma_f32_16x16x32_bf16 v[98:101], v[180:183], v[196:199], v[98:101]
	v_mfma_f32_16x16x32_bf16 v[86:89], v[172:175], v[230:233], v[86:89]
	v_mfma_f32_16x16x32_bf16 v[82:85], v[180:183], v[230:233], v[82:85]
	v_mfma_f32_16x16x32_bf16 v[70:73], v[172:175], v[238:241], v[70:73]
	v_mfma_f32_16x16x32_bf16 v[66:69], v[180:183], v[238:241], v[66:69]
	s_setprio 0
	s_barrier
	s_add_i32 s2, s38, s21
	v_lshl_add_u64 v[156:157], v[156:157], 0, s[42:43]
	s_mov_b32 m0, s2
	ds_read_b128 v[184:187], v166 offset:49152
	ds_read_b128 v[188:191], v166 offset:50176
	ds_read_b128 v[192:195], v166 offset:51200
	ds_read_b128 v[196:199], v166 offset:52224
	ds_read_b128 v[226:229], v166 offset:53248
	ds_read_b128 v[230:233], v166 offset:54272
	ds_read_b128 v[234:237], v166 offset:55296
	ds_read_b128 v[238:241], v166 offset:56320
	global_load_lds_dwordx4 v[156:157], off
	s_add_i32 m0, s2, 0x2000
	s_add_u32 s2, s28, 0x80080
	v_lshl_add_u64 v[156:157], v[200:201], 0, s[42:43]
	s_addc_u32 s3, s29, 0
	s_add_i32 s28, s39, s21
	global_load_lds_dwordx4 v[156:157], off
	v_lshl_add_u64 v[156:157], s[2:3], 0, v[132:133]
	s_mov_b32 m0, s28
	s_nop 0
	global_load_lds_dwordx4 v[156:157], off
	v_lshl_add_u64 v[156:157], s[2:3], 0, v[136:137]
	s_add_i32 m0, s28, 0x2000
	s_nop 0
	global_load_lds_dwordx4 v[156:157], off
	v_lshl_add_u64 v[156:157], v[206:207], 0, s[42:43]
	s_mov_b32 m0, s46
	s_nop 0
	global_load_lds_dwordx4 v[156:157], off
	v_lshl_add_u64 v[156:157], v[242:243], 0, s[42:43]
	s_mov_b32 m0, s48
	s_nop 0
	global_load_lds_dwordx4 v[156:157], off
	s_waitcnt vmcnt(8)
	s_waitcnt lgkmcnt(0)
	s_barrier
	s_setprio 1
	v_mfma_f32_16x16x32_bf16 v[62:65], v[140:143], v[184:187], v[62:65]
	v_mfma_f32_16x16x32_bf16 v[58:61], v[148:151], v[184:187], v[58:61]
	v_mfma_f32_16x16x32_bf16 v[46:49], v[140:143], v[192:195], v[46:49]
	v_mfma_f32_16x16x32_bf16 v[42:45], v[148:151], v[192:195], v[42:45]
	v_mfma_f32_16x16x32_bf16 v[30:33], v[140:143], v[226:229], v[30:33]
	v_mfma_f32_16x16x32_bf16 v[26:29], v[148:151], v[226:229], v[26:29]
	v_mfma_f32_16x16x32_bf16 v[14:17], v[140:143], v[234:237], v[14:17]
	v_mfma_f32_16x16x32_bf16 v[10:13], v[148:151], v[234:237], v[10:13]
	v_mfma_f32_16x16x32_bf16 v[62:65], v[144:147], v[188:191], v[62:65]
	v_mfma_f32_16x16x32_bf16 v[58:61], v[152:155], v[188:191], v[58:61]
	v_mfma_f32_16x16x32_bf16 v[46:49], v[144:147], v[196:199], v[46:49]
	v_mfma_f32_16x16x32_bf16 v[42:45], v[152:155], v[196:199], v[42:45]
	v_mfma_f32_16x16x32_bf16 v[30:33], v[144:147], v[230:233], v[30:33]
	v_mfma_f32_16x16x32_bf16 v[26:29], v[152:155], v[230:233], v[26:29]
	v_mfma_f32_16x16x32_bf16 v[14:17], v[144:147], v[238:241], v[14:17]
	v_mfma_f32_16x16x32_bf16 v[10:13], v[152:155], v[238:241], v[10:13]
	v_mfma_f32_16x16x32_bf16 v[54:57], v[168:171], v[184:187], v[54:57]
	v_mfma_f32_16x16x32_bf16 v[50:53], v[176:179], v[184:187], v[50:53]
	v_mfma_f32_16x16x32_bf16 v[38:41], v[168:171], v[192:195], v[38:41]
	v_mfma_f32_16x16x32_bf16 v[34:37], v[176:179], v[192:195], v[34:37]
	v_mfma_f32_16x16x32_bf16 v[22:25], v[168:171], v[226:229], v[22:25]
	v_mfma_f32_16x16x32_bf16 v[18:21], v[176:179], v[226:229], v[18:21]
	v_mfma_f32_16x16x32_bf16 v[6:9], v[168:171], v[234:237], v[6:9]
	v_mfma_f32_16x16x32_bf16 v[2:5], v[176:179], v[234:237], v[2:5]
	v_mfma_f32_16x16x32_bf16 v[54:57], v[172:175], v[188:191], v[54:57]
	v_mfma_f32_16x16x32_bf16 v[50:53], v[180:183], v[188:191], v[50:53]
	v_mfma_f32_16x16x32_bf16 v[38:41], v[172:175], v[196:199], v[38:41]
	v_mfma_f32_16x16x32_bf16 v[34:37], v[180:183], v[196:199], v[34:37]
	v_mfma_f32_16x16x32_bf16 v[22:25], v[172:175], v[230:233], v[22:25]
	v_mfma_f32_16x16x32_bf16 v[18:21], v[180:183], v[230:233], v[18:21]
	v_mfma_f32_16x16x32_bf16 v[6:9], v[172:175], v[238:241], v[6:9]
	v_mfma_f32_16x16x32_bf16 v[2:5], v[180:183], v[238:241], v[2:5]
	s_setprio 0
	s_barrier
	s_cmp_gt_u32 s56, 29
	s_cbranch_scc1 .LBB0_266
	s_mov_b32 s56, s22
	s_branch .LBB0_250

.LBB0_917:
	s_add_u32 s2, s28, s62
	s_addc_u32 s3, s29, s63
	s_add_u32 s78, s72, s62
	s_addc_u32 s79, s73, s63
	s_add_i32 s93, 0, 0x10000
	s_cmp_eq_u32 s9, s89
	s_cselect_b32 s3, s13, s3
	s_cselect_b32 s2, s22, s2
	s_cselect_b32 s79, s21, s79
	s_cselect_b32 s78, s88, s78
	s_add_i32 s95, 0, 0x14000
	v_add_u32_e32 v162, s93, v146
	v_add_u32_e32 v178, s95, v146
	ds_read_b128 v[150:153], v162
	ds_read_b128 v[154:157], v162 offset:1024
	ds_read_b128 v[158:161], v162 offset:2048
	ds_read_b128 v[162:165], v162 offset:3072
	ds_read_b128 v[166:169], v178
	ds_read_b128 v[170:173], v178 offset:1024
	ds_read_b128 v[174:177], v178 offset:2048
	ds_read_b128 v[178:181], v178 offset:3072
	v_lshl_add_u64 v[206:207], s[28:29], 0, v[142:143]
	s_add_i32 m0, s7, 0xc000
	ds_read_b128 v[182:185], v149
	ds_read_b128 v[186:189], v149 offset:1024
	ds_read_b128 v[190:193], v149 offset:2048
	ds_read_b128 v[194:197], v149 offset:3072
	ds_read_b128 v[198:201], v149 offset:4096
	ds_read_b128 v[230:233], v149 offset:5120
	ds_read_b128 v[234:237], v149 offset:6144
	ds_read_b128 v[238:241], v149 offset:7168
	global_load_lds_dwordx4 v[206:207], off
	v_lshl_add_u64 v[206:207], s[28:29], 0, v[140:141]
	s_add_i32 m0, s7, 0xe000
	s_nop 0
	global_load_lds_dwordx4 v[206:207], off
	s_waitcnt vmcnt(8)
	s_waitcnt lgkmcnt(0)
	s_barrier
	s_setprio 1
	v_mfma_f32_16x16x32_bf16 v[126:129], v[150:153], v[182:185], v[126:129]
	v_mfma_f32_16x16x32_bf16 v[122:125], v[158:161], v[182:185], v[122:125]
	v_mfma_f32_16x16x32_bf16 v[110:113], v[150:153], v[190:193], v[110:113]
	v_mfma_f32_16x16x32_bf16 v[106:109], v[158:161], v[190:193], v[106:109]
	v_mfma_f32_16x16x32_bf16 v[94:97], v[150:153], v[198:201], v[94:97]
	v_mfma_f32_16x16x32_bf16 v[90:93], v[158:161], v[198:201], v[90:93]
	v_mfma_f32_16x16x32_bf16 v[78:81], v[150:153], v[234:237], v[78:81]
	v_mfma_f32_16x16x32_bf16 v[74:77], v[158:161], v[234:237], v[74:77]
	v_mfma_f32_16x16x32_bf16 v[126:129], v[154:157], v[186:189], v[126:129]
	v_mfma_f32_16x16x32_bf16 v[122:125], v[162:165], v[186:189], v[122:125]
	v_mfma_f32_16x16x32_bf16 v[110:113], v[154:157], v[194:197], v[110:113]
	v_mfma_f32_16x16x32_bf16 v[106:109], v[162:165], v[194:197], v[106:109]
	v_mfma_f32_16x16x32_bf16 v[94:97], v[154:157], v[230:233], v[94:97]
	v_mfma_f32_16x16x32_bf16 v[90:93], v[162:165], v[230:233], v[90:93]
	v_mfma_f32_16x16x32_bf16 v[78:81], v[154:157], v[238:241], v[78:81]
	v_mfma_f32_16x16x32_bf16 v[74:77], v[162:165], v[238:241], v[74:77]
	v_mfma_f32_16x16x32_bf16 v[118:121], v[166:169], v[182:185], v[118:121]
	v_mfma_f32_16x16x32_bf16 v[114:117], v[174:177], v[182:185], v[114:117]
	v_mfma_f32_16x16x32_bf16 v[102:105], v[166:169], v[190:193], v[102:105]
	v_mfma_f32_16x16x32_bf16 v[98:101], v[174:177], v[190:193], v[98:101]
	v_mfma_f32_16x16x32_bf16 v[86:89], v[166:169], v[198:201], v[86:89]
	v_mfma_f32_16x16x32_bf16 v[82:85], v[174:177], v[198:201], v[82:85]
	v_mfma_f32_16x16x32_bf16 v[70:73], v[166:169], v[234:237], v[70:73]
	v_mfma_f32_16x16x32_bf16 v[66:69], v[174:177], v[234:237], v[66:69]
	v_mfma_f32_16x16x32_bf16 v[118:121], v[170:173], v[186:189], v[118:121]
	v_mfma_f32_16x16x32_bf16 v[114:117], v[178:181], v[186:189], v[114:117]
	v_mfma_f32_16x16x32_bf16 v[102:105], v[170:173], v[194:197], v[102:105]
	v_mfma_f32_16x16x32_bf16 v[98:101], v[178:181], v[194:197], v[98:101]
	v_mfma_f32_16x16x32_bf16 v[86:89], v[170:173], v[230:233], v[86:89]
	v_mfma_f32_16x16x32_bf16 v[82:85], v[178:181], v[230:233], v[82:85]
	v_mfma_f32_16x16x32_bf16 v[70:73], v[170:173], v[238:241], v[70:73]
	v_mfma_f32_16x16x32_bf16 v[66:69], v[178:181], v[238:241], v[66:69]
	s_setprio 0
	s_barrier
	s_add_i32 s93, s93, s56
	v_lshl_add_u64 v[206:207], s[78:79], 0, v[202:203]
	s_mov_b32 m0, s93
	ds_read_b128 v[182:185], v149 offset:16384
	ds_read_b128 v[186:189], v149 offset:17408
	ds_read_b128 v[190:193], v149 offset:18432
	ds_read_b128 v[194:197], v149 offset:19456
	ds_read_b128 v[198:201], v149 offset:20480
	ds_read_b128 v[230:233], v149 offset:21504
	ds_read_b128 v[234:237], v149 offset:22528
	ds_read_b128 v[238:241], v149 offset:23552
	global_load_lds_dwordx4 v[206:207], off
	s_add_i32 m0, s93, 0x2000
	s_add_u32 s96, s78, 0x80000
	v_lshl_add_u64 v[242:243], s[78:79], 0, v[134:135]
	s_addc_u32 s97, s79, 0
	s_add_i32 s93, s95, s56
	global_load_lds_dwordx4 v[242:243], off
	v_lshl_add_u64 v[244:245], s[96:97], 0, v[202:203]
	s_mov_b32 m0, s93
	v_lshl_add_u64 v[246:247], s[2:3], 0, v[132:133]
	global_load_lds_dwordx4 v[244:245], off
	v_lshl_add_u64 v[244:245], s[96:97], 0, v[134:135]
	s_add_i32 m0, s93, 0x2000
	s_nop 0
	global_load_lds_dwordx4 v[244:245], off
	v_lshl_add_u64 v[244:245], s[2:3], 0, v[130:131]
	s_mov_b32 m0, s7
	s_nop 0
	global_load_lds_dwordx4 v[244:245], off
	s_mov_b32 m0, s68
	s_nop 0
	global_load_lds_dwordx4 v[246:247], off
	s_waitcnt vmcnt(8)
	s_waitcnt lgkmcnt(0)
	s_barrier
	s_setprio 1
	v_mfma_f32_16x16x32_bf16 v[62:65], v[150:153], v[182:185], v[62:65]
	v_mfma_f32_16x16x32_bf16 v[58:61], v[158:161], v[182:185], v[58:61]
	v_mfma_f32_16x16x32_bf16 v[46:49], v[150:153], v[190:193], v[46:49]
	v_mfma_f32_16x16x32_bf16 v[42:45], v[158:161], v[190:193], v[42:45]
	v_mfma_f32_16x16x32_bf16 v[30:33], v[150:153], v[198:201], v[30:33]
	v_mfma_f32_16x16x32_bf16 v[26:29], v[158:161], v[198:201], v[26:29]
	v_mfma_f32_16x16x32_bf16 v[14:17], v[150:153], v[234:237], v[14:17]
	v_mfma_f32_16x16x32_bf16 v[10:13], v[158:161], v[234:237], v[10:13]
	v_mfma_f32_16x16x32_bf16 v[62:65], v[154:157], v[186:189], v[62:65]
	v_mfma_f32_16x16x32_bf16 v[58:61], v[162:165], v[186:189], v[58:61]
	v_mfma_f32_16x16x32_bf16 v[46:49], v[154:157], v[194:197], v[46:49]
	v_mfma_f32_16x16x32_bf16 v[42:45], v[162:165], v[194:197], v[42:45]
	v_mfma_f32_16x16x32_bf16 v[30:33], v[154:157], v[230:233], v[30:33]
	v_mfma_f32_16x16x32_bf16 v[26:29], v[162:165], v[230:233], v[26:29]
	v_mfma_f32_16x16x32_bf16 v[14:17], v[154:157], v[238:241], v[14:17]
	v_mfma_f32_16x16x32_bf16 v[10:13], v[162:165], v[238:241], v[10:13]
	v_mfma_f32_16x16x32_bf16 v[54:57], v[166:169], v[182:185], v[54:57]
	v_mfma_f32_16x16x32_bf16 v[50:53], v[174:177], v[182:185], v[50:53]
	v_mfma_f32_16x16x32_bf16 v[38:41], v[166:169], v[190:193], v[38:41]
	v_mfma_f32_16x16x32_bf16 v[34:37], v[174:177], v[190:193], v[34:37]
	v_mfma_f32_16x16x32_bf16 v[22:25], v[166:169], v[198:201], v[22:25]
	v_mfma_f32_16x16x32_bf16 v[18:21], v[174:177], v[198:201], v[18:21]
	v_mfma_f32_16x16x32_bf16 v[6:9], v[166:169], v[234:237], v[6:9]
	v_mfma_f32_16x16x32_bf16 v[2:5], v[174:177], v[234:237], v[2:5]
	v_mfma_f32_16x16x32_bf16 v[54:57], v[170:173], v[186:189], v[54:57]
	v_mfma_f32_16x16x32_bf16 v[50:53], v[178:181], v[186:189], v[50:53]
	v_mfma_f32_16x16x32_bf16 v[38:41], v[170:173], v[194:197], v[38:41]
	v_mfma_f32_16x16x32_bf16 v[34:37], v[178:181], v[194:197], v[34:37]
	v_mfma_f32_16x16x32_bf16 v[22:25], v[170:173], v[230:233], v[22:25]
	v_mfma_f32_16x16x32_bf16 v[18:21], v[178:181], v[230:233], v[18:21]
	v_mfma_f32_16x16x32_bf16 v[6:9], v[170:173], v[238:241], v[6:9]
	v_mfma_f32_16x16x32_bf16 v[2:5], v[178:181], v[238:241], v[2:5]
	s_setprio 0
	s_barrier
	s_add_i32 s93, 0, 0x18000
	s_add_i32 s95, 0, 0x1c000
	v_add_u32_e32 v162, s93, v146
	v_add_u32_e32 v178, s95, v146
	ds_read_b128 v[150:153], v162
	ds_read_b128 v[154:157], v162 offset:1024
	ds_read_b128 v[158:161], v162 offset:2048
	ds_read_b128 v[162:165], v162 offset:3072
	ds_read_b128 v[166:169], v178
	ds_read_b128 v[170:173], v178 offset:1024
	ds_read_b128 v[174:177], v178 offset:2048
	ds_read_b128 v[178:181], v178 offset:3072
	s_add_u32 s2, s2, 0x80000
	s_addc_u32 s3, s3, 0
	s_mov_b32 m0, s69
	v_lshl_add_u64 v[248:249], s[2:3], 0, v[130:131]
	ds_read_b128 v[182:185], v149 offset:32768
	ds_read_b128 v[186:189], v149 offset:33792
	ds_read_b128 v[190:193], v149 offset:34816
	ds_read_b128 v[194:197], v149 offset:35840
	ds_read_b128 v[198:201], v149 offset:36864
	ds_read_b128 v[230:233], v149 offset:37888
	ds_read_b128 v[234:237], v149 offset:38912
	ds_read_b128 v[238:241], v149 offset:39936
	global_load_lds_dwordx4 v[248:249], off
	v_lshl_add_u64 v[248:249], s[2:3], 0, v[132:133]
	s_mov_b32 m0, s77
	s_nop 0
	global_load_lds_dwordx4 v[248:249], off
	s_waitcnt vmcnt(8)
	s_waitcnt lgkmcnt(0)
	s_barrier
	s_setprio 1
	v_mfma_f32_16x16x32_bf16 v[126:129], v[150:153], v[182:185], v[126:129]
	v_mfma_f32_16x16x32_bf16 v[122:125], v[158:161], v[182:185], v[122:125]
	v_mfma_f32_16x16x32_bf16 v[110:113], v[150:153], v[190:193], v[110:113]
	v_mfma_f32_16x16x32_bf16 v[106:109], v[158:161], v[190:193], v[106:109]
	v_mfma_f32_16x16x32_bf16 v[94:97], v[150:153], v[198:201], v[94:97]
	v_mfma_f32_16x16x32_bf16 v[90:93], v[158:161], v[198:201], v[90:93]
	v_mfma_f32_16x16x32_bf16 v[78:81], v[150:153], v[234:237], v[78:81]
	v_mfma_f32_16x16x32_bf16 v[74:77], v[158:161], v[234:237], v[74:77]
	v_mfma_f32_16x16x32_bf16 v[126:129], v[154:157], v[186:189], v[126:129]
	v_mfma_f32_16x16x32_bf16 v[122:125], v[162:165], v[186:189], v[122:125]
	v_mfma_f32_16x16x32_bf16 v[110:113], v[154:157], v[194:197], v[110:113]
	v_mfma_f32_16x16x32_bf16 v[106:109], v[162:165], v[194:197], v[106:109]
	v_mfma_f32_16x16x32_bf16 v[94:97], v[154:157], v[230:233], v[94:97]
	v_mfma_f32_16x16x32_bf16 v[90:93], v[162:165], v[230:233], v[90:93]
	v_mfma_f32_16x16x32_bf16 v[78:81], v[154:157], v[238:241], v[78:81]
	v_mfma_f32_16x16x32_bf16 v[74:77], v[162:165], v[238:241], v[74:77]
	v_mfma_f32_16x16x32_bf16 v[118:121], v[166:169], v[182:185], v[118:121]
	v_mfma_f32_16x16x32_bf16 v[114:117], v[174:177], v[182:185], v[114:117]
	v_mfma_f32_16x16x32_bf16 v[102:105], v[166:169], v[190:193], v[102:105]
	v_mfma_f32_16x16x32_bf16 v[98:101], v[174:177], v[190:193], v[98:101]
	v_mfma_f32_16x16x32_bf16 v[86:89], v[166:169], v[198:201], v[86:89]
	v_mfma_f32_16x16x32_bf16 v[82:85], v[174:177], v[198:201], v[82:85]
	v_mfma_f32_16x16x32_bf16 v[70:73], v[166:169], v[234:237], v[70:73]
	v_mfma_f32_16x16x32_bf16 v[66:69], v[174:177], v[234:237], v[66:69]
	v_mfma_f32_16x16x32_bf16 v[118:121], v[170:173], v[186:189], v[118:121]
	v_mfma_f32_16x16x32_bf16 v[114:117], v[178:181], v[186:189], v[114:117]
	v_mfma_f32_16x16x32_bf16 v[102:105], v[170:173], v[194:197], v[102:105]
	v_mfma_f32_16x16x32_bf16 v[98:101], v[178:181], v[194:197], v[98:101]
	v_mfma_f32_16x16x32_bf16 v[86:89], v[170:173], v[230:233], v[86:89]
	v_mfma_f32_16x16x32_bf16 v[82:85], v[178:181], v[230:233], v[82:85]
	v_mfma_f32_16x16x32_bf16 v[70:73], v[170:173], v[238:241], v[70:73]
	v_mfma_f32_16x16x32_bf16 v[66:69], v[178:181], v[238:241], v[66:69]
	s_setprio 0
	s_barrier
	s_add_i32 s2, s93, s56
	v_lshl_add_u64 v[206:207], v[206:207], 0, s[42:43]
	s_mov_b32 m0, s2
	ds_read_b128 v[182:185], v149 offset:49152
	ds_read_b128 v[186:189], v149 offset:50176
	ds_read_b128 v[190:193], v149 offset:51200
	ds_read_b128 v[194:197], v149 offset:52224
	ds_read_b128 v[198:201], v149 offset:53248
	ds_read_b128 v[230:233], v149 offset:54272
	ds_read_b128 v[234:237], v149 offset:55296
	ds_read_b128 v[238:241], v149 offset:56320
	global_load_lds_dwordx4 v[206:207], off
	s_add_i32 m0, s2, 0x2000
	s_add_u32 s2, s78, 0x80080
	v_lshl_add_u64 v[206:207], v[242:243], 0, s[42:43]
	s_addc_u32 s3, s79, 0
	s_add_i32 s78, s95, s56
	global_load_lds_dwordx4 v[206:207], off
	v_lshl_add_u64 v[206:207], s[2:3], 0, v[202:203]
	s_mov_b32 m0, s78
	s_nop 0
	global_load_lds_dwordx4 v[206:207], off
	v_lshl_add_u64 v[206:207], s[2:3], 0, v[134:135]
	s_add_i32 m0, s78, 0x2000
	s_nop 0
	global_load_lds_dwordx4 v[206:207], off
	v_lshl_add_u64 v[206:207], v[244:245], 0, s[42:43]
	s_mov_b32 m0, s83
	s_nop 0
	global_load_lds_dwordx4 v[206:207], off
	v_lshl_add_u64 v[206:207], v[246:247], 0, s[42:43]
	s_mov_b32 m0, s86
	s_nop 0
	global_load_lds_dwordx4 v[206:207], off
	s_waitcnt vmcnt(8)
	s_waitcnt lgkmcnt(0)
	s_barrier
	s_setprio 1
	v_mfma_f32_16x16x32_bf16 v[62:65], v[150:153], v[182:185], v[62:65]
	v_mfma_f32_16x16x32_bf16 v[58:61], v[158:161], v[182:185], v[58:61]
	v_mfma_f32_16x16x32_bf16 v[46:49], v[150:153], v[190:193], v[46:49]
	v_mfma_f32_16x16x32_bf16 v[42:45], v[158:161], v[190:193], v[42:45]
	v_mfma_f32_16x16x32_bf16 v[30:33], v[150:153], v[198:201], v[30:33]
	v_mfma_f32_16x16x32_bf16 v[26:29], v[158:161], v[198:201], v[26:29]
	v_mfma_f32_16x16x32_bf16 v[14:17], v[150:153], v[234:237], v[14:17]
	v_mfma_f32_16x16x32_bf16 v[10:13], v[158:161], v[234:237], v[10:13]
	v_mfma_f32_16x16x32_bf16 v[62:65], v[154:157], v[186:189], v[62:65]
	v_mfma_f32_16x16x32_bf16 v[58:61], v[162:165], v[186:189], v[58:61]
	v_mfma_f32_16x16x32_bf16 v[46:49], v[154:157], v[194:197], v[46:49]
	v_mfma_f32_16x16x32_bf16 v[42:45], v[162:165], v[194:197], v[42:45]
	v_mfma_f32_16x16x32_bf16 v[30:33], v[154:157], v[230:233], v[30:33]
	v_mfma_f32_16x16x32_bf16 v[26:29], v[162:165], v[230:233], v[26:29]
	v_mfma_f32_16x16x32_bf16 v[14:17], v[154:157], v[238:241], v[14:17]
	v_mfma_f32_16x16x32_bf16 v[10:13], v[162:165], v[238:241], v[10:13]
	v_mfma_f32_16x16x32_bf16 v[54:57], v[166:169], v[182:185], v[54:57]
	v_mfma_f32_16x16x32_bf16 v[50:53], v[174:177], v[182:185], v[50:53]
	v_mfma_f32_16x16x32_bf16 v[38:41], v[166:169], v[190:193], v[38:41]
	v_mfma_f32_16x16x32_bf16 v[34:37], v[174:177], v[190:193], v[34:37]
	v_mfma_f32_16x16x32_bf16 v[22:25], v[166:169], v[198:201], v[22:25]
	v_mfma_f32_16x16x32_bf16 v[18:21], v[174:177], v[198:201], v[18:21]
	v_mfma_f32_16x16x32_bf16 v[6:9], v[166:169], v[234:237], v[6:9]
	v_mfma_f32_16x16x32_bf16 v[2:5], v[174:177], v[234:237], v[2:5]
	v_mfma_f32_16x16x32_bf16 v[54:57], v[170:173], v[186:189], v[54:57]
	v_mfma_f32_16x16x32_bf16 v[50:53], v[178:181], v[186:189], v[50:53]
	v_mfma_f32_16x16x32_bf16 v[38:41], v[170:173], v[194:197], v[38:41]
	v_mfma_f32_16x16x32_bf16 v[34:37], v[178:181], v[194:197], v[34:37]
	v_mfma_f32_16x16x32_bf16 v[22:25], v[170:173], v[230:233], v[22:25]
	v_mfma_f32_16x16x32_bf16 v[18:21], v[178:181], v[230:233], v[18:21]
	v_mfma_f32_16x16x32_bf16 v[6:9], v[170:173], v[238:241], v[6:9]
	v_mfma_f32_16x16x32_bf16 v[2:5], v[178:181], v[238:241], v[2:5]
	s_setprio 0
	s_barrier
	s_add_i32 s2, s89, 2
	s_add_u32 s62, s62, 0x100
	s_addc_u32 s63, s63, 0
	v_lshl_add_u64 v[142:143], v[142:143], 0, s[70:71]
	v_lshl_add_u64 v[140:141], v[140:141], 0, s[70:71]
	s_cmp_ge_i32 s89, s9
	s_mov_b32 s89, s2
	s_cbranch_scc0 .LBB0_917
	s_and_b64 vcc, exec, s[30:31]
	s_cbranch_vccz .LBB0_920
	s_barrier

.LBB0_1049:
	s_or_b32 s22, s88, 1
	s_lshl_b64 s[0:1], s[22:23], 7
	s_add_u32 s38, s6, s0
	s_addc_u32 s39, s7, s1
	s_add_i32 s22, s88, 2
	s_lshl_b64 s[0:1], s[22:23], 7
	s_add_u32 s62, s6, s0
	s_addc_u32 s63, s7, s1
	s_and_b64 s[2:3], s[28:29], exec
	s_cselect_b32 s3, s63, s77
	s_cselect_b32 s2, s62, s58
	s_add_u32 s62, s86, s0
	s_addc_u32 s63, s87, s1
	s_and_b64 s[0:1], s[28:29], exec
	s_cselect_b32 s29, s63, s93
	s_cselect_b32 s28, s62, s89
	s_add_i32 s62, 0, 0x10000
	v_add_u32_e32 v145, s62, v142
	s_add_i32 s63, 0, 0x14000
	ds_read_b128 v[136:139], v145
	ds_read_b128 v[146:149], v145 offset:1024
	ds_read_b128 v[150:153], v145 offset:2048
	ds_read_b128 v[154:157], v145 offset:3072
	v_add_u32_e32 v145, s63, v142
	ds_read_b128 v[158:161], v145
	ds_read_b128 v[162:165], v145 offset:1024
	ds_read_b128 v[166:169], v145 offset:2048
	ds_read_b128 v[170:173], v145 offset:3072
	s_add_u32 s0, s38, 0x80000
	s_addc_u32 s1, s39, 0
	v_lshl_add_u64 v[206:207], s[0:1], 0, v[130:131]
	s_add_i32 m0, s95, 0xc000
	ds_read_b128 v[174:177], v144
	ds_read_b128 v[178:181], v144 offset:1024
	ds_read_b128 v[182:185], v144 offset:2048
	ds_read_b128 v[186:189], v144 offset:3072
	ds_read_b128 v[190:193], v144 offset:4096
	ds_read_b128 v[194:197], v144 offset:5120
	ds_read_b128 v[198:201], v144 offset:6144
	ds_read_b128 v[226:229], v144 offset:7168
	global_load_lds_dwordx4 v[206:207], off
	v_lshl_add_u64 v[206:207], s[0:1], 0, v[132:133]
	s_add_i32 m0, s95, 0xe000
	s_nop 0
	global_load_lds_dwordx4 v[206:207], off
	s_waitcnt vmcnt(8)
	s_waitcnt lgkmcnt(0)
	s_barrier
	s_setprio 1
	v_mfma_f32_16x16x32_bf16 v[126:129], v[136:139], v[174:177], v[126:129]
	v_mfma_f32_16x16x32_bf16 v[114:117], v[150:153], v[174:177], v[114:117]
	v_mfma_f32_16x16x32_bf16 v[110:113], v[136:139], v[182:185], v[110:113]
	v_mfma_f32_16x16x32_bf16 v[98:101], v[150:153], v[182:185], v[98:101]
	v_mfma_f32_16x16x32_bf16 v[94:97], v[136:139], v[190:193], v[94:97]
	v_mfma_f32_16x16x32_bf16 v[82:85], v[150:153], v[190:193], v[82:85]
	v_mfma_f32_16x16x32_bf16 v[78:81], v[136:139], v[198:201], v[78:81]
	v_mfma_f32_16x16x32_bf16 v[66:69], v[150:153], v[198:201], v[66:69]
	v_mfma_f32_16x16x32_bf16 v[126:129], v[146:149], v[178:181], v[126:129]
	v_mfma_f32_16x16x32_bf16 v[114:117], v[154:157], v[178:181], v[114:117]
	v_mfma_f32_16x16x32_bf16 v[110:113], v[146:149], v[186:189], v[110:113]
	v_mfma_f32_16x16x32_bf16 v[98:101], v[154:157], v[186:189], v[98:101]
	v_mfma_f32_16x16x32_bf16 v[94:97], v[146:149], v[194:197], v[94:97]
	v_mfma_f32_16x16x32_bf16 v[82:85], v[154:157], v[194:197], v[82:85]
	v_mfma_f32_16x16x32_bf16 v[78:81], v[146:149], v[226:229], v[78:81]
	v_mfma_f32_16x16x32_bf16 v[66:69], v[154:157], v[226:229], v[66:69]
	v_mfma_f32_16x16x32_bf16 v[122:125], v[158:161], v[174:177], v[122:125]
	v_mfma_f32_16x16x32_bf16 v[118:121], v[166:169], v[174:177], v[118:121]
	v_mfma_f32_16x16x32_bf16 v[106:109], v[158:161], v[182:185], v[106:109]
	v_mfma_f32_16x16x32_bf16 v[102:105], v[166:169], v[182:185], v[102:105]
	v_mfma_f32_16x16x32_bf16 v[90:93], v[158:161], v[190:193], v[90:93]
	v_mfma_f32_16x16x32_bf16 v[86:89], v[166:169], v[190:193], v[86:89]
	v_mfma_f32_16x16x32_bf16 v[74:77], v[158:161], v[198:201], v[74:77]
	v_mfma_f32_16x16x32_bf16 v[70:73], v[166:169], v[198:201], v[70:73]
	v_mfma_f32_16x16x32_bf16 v[122:125], v[162:165], v[178:181], v[122:125]
	v_mfma_f32_16x16x32_bf16 v[118:121], v[170:173], v[178:181], v[118:121]
	v_mfma_f32_16x16x32_bf16 v[106:109], v[162:165], v[186:189], v[106:109]
	v_mfma_f32_16x16x32_bf16 v[102:105], v[170:173], v[186:189], v[102:105]
	v_mfma_f32_16x16x32_bf16 v[90:93], v[162:165], v[194:197], v[90:93]
	v_mfma_f32_16x16x32_bf16 v[86:89], v[170:173], v[194:197], v[86:89]
	v_mfma_f32_16x16x32_bf16 v[74:77], v[162:165], v[226:229], v[74:77]
	v_mfma_f32_16x16x32_bf16 v[70:73], v[170:173], v[226:229], v[70:73]
	s_setprio 0
	s_barrier
	s_add_i32 s0, s62, s75
	v_lshl_add_u64 v[206:207], s[28:29], 0, v[202:203]
	s_mov_b32 m0, s0
	ds_read_b128 v[174:177], v144 offset:16384
	ds_read_b128 v[178:181], v144 offset:17408
	ds_read_b128 v[182:185], v144 offset:18432
	ds_read_b128 v[186:189], v144 offset:19456
	ds_read_b128 v[190:193], v144 offset:20480
	ds_read_b128 v[194:197], v144 offset:21504
	ds_read_b128 v[198:201], v144 offset:22528
	ds_read_b128 v[226:229], v144 offset:23552
	global_load_lds_dwordx4 v[206:207], off
	s_add_i32 m0, s0, 0x2000
	s_add_u32 s0, s28, 0x80000
	v_lshl_add_u64 v[230:231], s[28:29], 0, v[134:135]
	s_addc_u32 s1, s29, 0
	s_add_i32 s38, s63, s75
	global_load_lds_dwordx4 v[230:231], off
	v_lshl_add_u64 v[232:233], s[0:1], 0, v[202:203]
	s_mov_b32 m0, s38
	v_lshl_add_u64 v[234:235], s[2:3], 0, v[132:133]
	global_load_lds_dwordx4 v[232:233], off
	v_lshl_add_u64 v[232:233], s[0:1], 0, v[134:135]
	s_add_i32 m0, s38, 0x2000
	s_nop 0
	global_load_lds_dwordx4 v[232:233], off
	v_lshl_add_u64 v[232:233], s[2:3], 0, v[130:131]
	s_mov_b32 m0, s95
	s_nop 0
	global_load_lds_dwordx4 v[232:233], off
	s_mov_b32 m0, s97
	s_nop 0
	global_load_lds_dwordx4 v[234:235], off
	s_waitcnt vmcnt(8)
	s_waitcnt lgkmcnt(0)
	s_barrier
	s_setprio 1
	v_mfma_f32_16x16x32_bf16 v[62:65], v[136:139], v[174:177], v[62:65]
	v_mfma_f32_16x16x32_bf16 v[50:53], v[150:153], v[174:177], v[50:53]
	v_mfma_f32_16x16x32_bf16 v[46:49], v[136:139], v[182:185], v[46:49]
	v_mfma_f32_16x16x32_bf16 v[34:37], v[150:153], v[182:185], v[34:37]
	v_mfma_f32_16x16x32_bf16 v[30:33], v[136:139], v[190:193], v[30:33]
	v_mfma_f32_16x16x32_bf16 v[18:21], v[150:153], v[190:193], v[18:21]
	v_mfma_f32_16x16x32_bf16 v[14:17], v[136:139], v[198:201], v[14:17]
	v_mfma_f32_16x16x32_bf16 v[6:9], v[150:153], v[198:201], v[6:9]
	v_mfma_f32_16x16x32_bf16 v[62:65], v[146:149], v[178:181], v[62:65]
	v_mfma_f32_16x16x32_bf16 v[50:53], v[154:157], v[178:181], v[50:53]
	v_mfma_f32_16x16x32_bf16 v[46:49], v[146:149], v[186:189], v[46:49]
	v_mfma_f32_16x16x32_bf16 v[34:37], v[154:157], v[186:189], v[34:37]
	v_mfma_f32_16x16x32_bf16 v[30:33], v[146:149], v[194:197], v[30:33]
	v_mfma_f32_16x16x32_bf16 v[18:21], v[154:157], v[194:197], v[18:21]
	v_mfma_f32_16x16x32_bf16 v[14:17], v[146:149], v[226:229], v[14:17]
	v_mfma_f32_16x16x32_bf16 v[6:9], v[154:157], v[226:229], v[6:9]
	v_mfma_f32_16x16x32_bf16 v[58:61], v[158:161], v[174:177], v[58:61]
	v_mfma_f32_16x16x32_bf16 v[54:57], v[166:169], v[174:177], v[54:57]
	v_mfma_f32_16x16x32_bf16 v[42:45], v[158:161], v[182:185], v[42:45]
	v_mfma_f32_16x16x32_bf16 v[38:41], v[166:169], v[182:185], v[38:41]
	v_mfma_f32_16x16x32_bf16 v[26:29], v[158:161], v[190:193], v[26:29]
	v_mfma_f32_16x16x32_bf16 v[22:25], v[166:169], v[190:193], v[22:25]
	v_mfma_f32_16x16x32_bf16 v[10:13], v[158:161], v[198:201], v[10:13]
	v_mfma_f32_16x16x32_bf16 v[2:5], v[166:169], v[198:201], v[2:5]
	v_mfma_f32_16x16x32_bf16 v[58:61], v[162:165], v[178:181], v[58:61]
	v_mfma_f32_16x16x32_bf16 v[54:57], v[170:173], v[178:181], v[54:57]
	v_mfma_f32_16x16x32_bf16 v[42:45], v[162:165], v[186:189], v[42:45]
	v_mfma_f32_16x16x32_bf16 v[38:41], v[170:173], v[186:189], v[38:41]
	v_mfma_f32_16x16x32_bf16 v[26:29], v[162:165], v[194:197], v[26:29]
	v_mfma_f32_16x16x32_bf16 v[22:25], v[170:173], v[194:197], v[22:25]
	v_mfma_f32_16x16x32_bf16 v[10:13], v[162:165], v[226:229], v[10:13]
	v_mfma_f32_16x16x32_bf16 v[2:5], v[170:173], v[226:229], v[2:5]
	s_setprio 0
	s_barrier
	s_add_i32 s38, 0, 0x18000
	v_add_u32_e32 v145, s38, v142
	s_add_i32 s39, 0, 0x1c000
	ds_read_b128 v[136:139], v145
	ds_read_b128 v[146:149], v145 offset:1024
	ds_read_b128 v[150:153], v145 offset:2048
	ds_read_b128 v[154:157], v145 offset:3072
	v_add_u32_e32 v145, s39, v142
	ds_read_b128 v[158:161], v145
	ds_read_b128 v[162:165], v145 offset:1024
	ds_read_b128 v[166:169], v145 offset:2048
	ds_read_b128 v[170:173], v145 offset:3072
	s_add_u32 s0, s2, 0x80000
	s_addc_u32 s1, s3, 0
	s_mov_b32 m0, s46
	v_lshl_add_u64 v[236:237], s[0:1], 0, v[130:131]
	ds_read_b128 v[174:177], v144 offset:32768
	ds_read_b128 v[178:181], v144 offset:33792
	ds_read_b128 v[182:185], v144 offset:34816
	ds_read_b128 v[186:189], v144 offset:35840
	ds_read_b128 v[190:193], v144 offset:36864
	ds_read_b128 v[194:197], v144 offset:37888
	ds_read_b128 v[198:201], v144 offset:38912
	ds_read_b128 v[226:229], v144 offset:39936
	global_load_lds_dwordx4 v[236:237], off
	v_lshl_add_u64 v[236:237], s[0:1], 0, v[132:133]
	s_mov_b32 m0, s48
	s_nop 0
	global_load_lds_dwordx4 v[236:237], off
	s_waitcnt vmcnt(8)
	s_waitcnt lgkmcnt(0)
	s_barrier
	s_setprio 1
	v_mfma_f32_16x16x32_bf16 v[126:129], v[136:139], v[174:177], v[126:129]
	v_mfma_f32_16x16x32_bf16 v[114:117], v[150:153], v[174:177], v[114:117]
	v_mfma_f32_16x16x32_bf16 v[110:113], v[136:139], v[182:185], v[110:113]
	v_mfma_f32_16x16x32_bf16 v[98:101], v[150:153], v[182:185], v[98:101]
	v_mfma_f32_16x16x32_bf16 v[94:97], v[136:139], v[190:193], v[94:97]
	v_mfma_f32_16x16x32_bf16 v[82:85], v[150:153], v[190:193], v[82:85]
	v_mfma_f32_16x16x32_bf16 v[78:81], v[136:139], v[198:201], v[78:81]
	v_mfma_f32_16x16x32_bf16 v[66:69], v[150:153], v[198:201], v[66:69]
	v_mfma_f32_16x16x32_bf16 v[126:129], v[146:149], v[178:181], v[126:129]
	v_mfma_f32_16x16x32_bf16 v[114:117], v[154:157], v[178:181], v[114:117]
	v_mfma_f32_16x16x32_bf16 v[110:113], v[146:149], v[186:189], v[110:113]
	v_mfma_f32_16x16x32_bf16 v[98:101], v[154:157], v[186:189], v[98:101]
	v_mfma_f32_16x16x32_bf16 v[94:97], v[146:149], v[194:197], v[94:97]
	v_mfma_f32_16x16x32_bf16 v[82:85], v[154:157], v[194:197], v[82:85]
	v_mfma_f32_16x16x32_bf16 v[78:81], v[146:149], v[226:229], v[78:81]
	v_mfma_f32_16x16x32_bf16 v[66:69], v[154:157], v[226:229], v[66:69]
	v_mfma_f32_16x16x32_bf16 v[122:125], v[158:161], v[174:177], v[122:125]
	v_mfma_f32_16x16x32_bf16 v[118:121], v[166:169], v[174:177], v[118:121]
	v_mfma_f32_16x16x32_bf16 v[106:109], v[158:161], v[182:185], v[106:109]
	v_mfma_f32_16x16x32_bf16 v[102:105], v[166:169], v[182:185], v[102:105]
	v_mfma_f32_16x16x32_bf16 v[90:93], v[158:161], v[190:193], v[90:93]
	v_mfma_f32_16x16x32_bf16 v[86:89], v[166:169], v[190:193], v[86:89]
	v_mfma_f32_16x16x32_bf16 v[74:77], v[158:161], v[198:201], v[74:77]
	v_mfma_f32_16x16x32_bf16 v[70:73], v[166:169], v[198:201], v[70:73]
	v_mfma_f32_16x16x32_bf16 v[122:125], v[162:165], v[178:181], v[122:125]
	v_mfma_f32_16x16x32_bf16 v[118:121], v[170:173], v[178:181], v[118:121]
	v_mfma_f32_16x16x32_bf16 v[106:109], v[162:165], v[186:189], v[106:109]
	v_mfma_f32_16x16x32_bf16 v[102:105], v[170:173], v[186:189], v[102:105]
	v_mfma_f32_16x16x32_bf16 v[90:93], v[162:165], v[194:197], v[90:93]
	v_mfma_f32_16x16x32_bf16 v[86:89], v[170:173], v[194:197], v[86:89]
	v_mfma_f32_16x16x32_bf16 v[74:77], v[162:165], v[226:229], v[74:77]
	v_mfma_f32_16x16x32_bf16 v[70:73], v[170:173], v[226:229], v[70:73]
	s_setprio 0
	s_barrier
	s_add_i32 s0, s38, s75
	v_lshl_add_u64 v[206:207], v[206:207], 0, s[42:43]
	s_mov_b32 m0, s0
	ds_read_b128 v[174:177], v144 offset:49152
	ds_read_b128 v[178:181], v144 offset:50176
	ds_read_b128 v[182:185], v144 offset:51200
	ds_read_b128 v[186:189], v144 offset:52224
	ds_read_b128 v[190:193], v144 offset:53248
	ds_read_b128 v[194:197], v144 offset:54272
	ds_read_b128 v[198:201], v144 offset:55296
	ds_read_b128 v[226:229], v144 offset:56320
	global_load_lds_dwordx4 v[206:207], off
	s_add_i32 m0, s0, 0x2000
	s_add_u32 s0, s28, 0x80080
	v_lshl_add_u64 v[206:207], v[230:231], 0, s[42:43]
	s_addc_u32 s1, s29, 0
	s_add_i32 s2, s39, s75
	global_load_lds_dwordx4 v[206:207], off
	v_lshl_add_u64 v[206:207], s[0:1], 0, v[202:203]
	s_mov_b32 m0, s2
	s_nop 0
	global_load_lds_dwordx4 v[206:207], off
	v_lshl_add_u64 v[206:207], s[0:1], 0, v[134:135]
	s_add_i32 m0, s2, 0x2000
	s_nop 0
	global_load_lds_dwordx4 v[206:207], off
	v_lshl_add_u64 v[206:207], v[232:233], 0, s[42:43]
	s_mov_b32 m0, s30
	s_nop 0
	global_load_lds_dwordx4 v[206:207], off
	v_lshl_add_u64 v[206:207], v[234:235], 0, s[42:43]
	s_mov_b32 m0, s31
	s_nop 0
	global_load_lds_dwordx4 v[206:207], off
	s_waitcnt vmcnt(8)
	s_waitcnt lgkmcnt(0)
	s_barrier
	s_setprio 1
	v_mfma_f32_16x16x32_bf16 v[62:65], v[136:139], v[174:177], v[62:65]
	v_mfma_f32_16x16x32_bf16 v[50:53], v[150:153], v[174:177], v[50:53]
	v_mfma_f32_16x16x32_bf16 v[46:49], v[136:139], v[182:185], v[46:49]
	v_mfma_f32_16x16x32_bf16 v[34:37], v[150:153], v[182:185], v[34:37]
	v_mfma_f32_16x16x32_bf16 v[30:33], v[136:139], v[190:193], v[30:33]
	v_mfma_f32_16x16x32_bf16 v[18:21], v[150:153], v[190:193], v[18:21]
	v_mfma_f32_16x16x32_bf16 v[14:17], v[136:139], v[198:201], v[14:17]
	v_mfma_f32_16x16x32_bf16 v[6:9], v[150:153], v[198:201], v[6:9]
	v_mfma_f32_16x16x32_bf16 v[62:65], v[146:149], v[178:181], v[62:65]
	v_mfma_f32_16x16x32_bf16 v[50:53], v[154:157], v[178:181], v[50:53]
	v_mfma_f32_16x16x32_bf16 v[46:49], v[146:149], v[186:189], v[46:49]
	v_mfma_f32_16x16x32_bf16 v[34:37], v[154:157], v[186:189], v[34:37]
	v_mfma_f32_16x16x32_bf16 v[30:33], v[146:149], v[194:197], v[30:33]
	v_mfma_f32_16x16x32_bf16 v[18:21], v[154:157], v[194:197], v[18:21]
	v_mfma_f32_16x16x32_bf16 v[14:17], v[146:149], v[226:229], v[14:17]
	v_mfma_f32_16x16x32_bf16 v[6:9], v[154:157], v[226:229], v[6:9]
	v_mfma_f32_16x16x32_bf16 v[58:61], v[158:161], v[174:177], v[58:61]
	v_mfma_f32_16x16x32_bf16 v[54:57], v[166:169], v[174:177], v[54:57]
	v_mfma_f32_16x16x32_bf16 v[42:45], v[158:161], v[182:185], v[42:45]
	v_mfma_f32_16x16x32_bf16 v[38:41], v[166:169], v[182:185], v[38:41]
	v_mfma_f32_16x16x32_bf16 v[26:29], v[158:161], v[190:193], v[26:29]
	v_mfma_f32_16x16x32_bf16 v[22:25], v[166:169], v[190:193], v[22:25]
	v_mfma_f32_16x16x32_bf16 v[10:13], v[158:161], v[198:201], v[10:13]
	v_mfma_f32_16x16x32_bf16 v[2:5], v[166:169], v[198:201], v[2:5]
	v_mfma_f32_16x16x32_bf16 v[58:61], v[162:165], v[178:181], v[58:61]
	v_mfma_f32_16x16x32_bf16 v[54:57], v[170:173], v[178:181], v[54:57]
	v_mfma_f32_16x16x32_bf16 v[42:45], v[162:165], v[186:189], v[42:45]
	v_mfma_f32_16x16x32_bf16 v[38:41], v[170:173], v[186:189], v[38:41]
	v_mfma_f32_16x16x32_bf16 v[26:29], v[162:165], v[194:197], v[26:29]
	v_mfma_f32_16x16x32_bf16 v[22:25], v[170:173], v[194:197], v[22:25]
	v_mfma_f32_16x16x32_bf16 v[10:13], v[162:165], v[226:229], v[10:13]
	v_mfma_f32_16x16x32_bf16 v[2:5], v[170:173], v[226:229], v[2:5]
	s_setprio 0
	s_barrier
	s_cmp_gt_u32 s88, 29
	s_mov_b32 s88, s22
	s_cbranch_scc1 .LBB0_1061

.LBB0_1247:
	s_add_u32 s1, s72, s28
	s_addc_u32 s2, s73, s29
	s_add_u32 s22, s8, s28
	s_addc_u32 s38, s9, s29
	s_add_i32 s88, 0, 0x10000
	s_cmp_eq_u32 s91, s0
	s_cselect_b32 s3, s45, s2
	s_cselect_b32 s2, s44, s1
	s_cselect_b32 s39, s75, s38
	s_cselect_b32 s38, s74, s22
	s_add_i32 s1, 0, 0x14000
	v_add_u32_e32 v162, s88, v146
	v_add_u32_e32 v178, s1, v146
	ds_read_b128 v[150:153], v162
	ds_read_b128 v[154:157], v162 offset:1024
	ds_read_b128 v[158:161], v162 offset:2048
	ds_read_b128 v[162:165], v162 offset:3072
	ds_read_b128 v[166:169], v178
	ds_read_b128 v[170:173], v178 offset:1024
	ds_read_b128 v[174:177], v178 offset:2048
	ds_read_b128 v[178:181], v178 offset:3072
	v_lshl_add_u64 v[206:207], s[72:73], 0, v[142:143]
	s_add_i32 m0, s62, 0xc000
	ds_read_b128 v[182:185], v149
	ds_read_b128 v[186:189], v149 offset:1024
	ds_read_b128 v[190:193], v149 offset:2048
	ds_read_b128 v[194:197], v149 offset:3072
	ds_read_b128 v[198:201], v149 offset:4096
	ds_read_b128 v[230:233], v149 offset:5120
	ds_read_b128 v[234:237], v149 offset:6144
	ds_read_b128 v[238:241], v149 offset:7168
	global_load_lds_dwordx4 v[206:207], off
	v_lshl_add_u64 v[206:207], s[72:73], 0, v[140:141]
	s_add_i32 m0, s62, 0xe000
	s_nop 0
	global_load_lds_dwordx4 v[206:207], off
	s_waitcnt vmcnt(8)
	s_waitcnt lgkmcnt(0)
	s_barrier
	s_setprio 1
	v_mfma_f32_16x16x32_bf16 v[126:129], v[150:153], v[182:185], v[126:129]
	v_mfma_f32_16x16x32_bf16 v[122:125], v[158:161], v[182:185], v[122:125]
	v_mfma_f32_16x16x32_bf16 v[110:113], v[150:153], v[190:193], v[110:113]
	v_mfma_f32_16x16x32_bf16 v[106:109], v[158:161], v[190:193], v[106:109]
	v_mfma_f32_16x16x32_bf16 v[94:97], v[150:153], v[198:201], v[94:97]
	v_mfma_f32_16x16x32_bf16 v[90:93], v[158:161], v[198:201], v[90:93]
	v_mfma_f32_16x16x32_bf16 v[78:81], v[150:153], v[234:237], v[78:81]
	v_mfma_f32_16x16x32_bf16 v[74:77], v[158:161], v[234:237], v[74:77]
	v_mfma_f32_16x16x32_bf16 v[126:129], v[154:157], v[186:189], v[126:129]
	v_mfma_f32_16x16x32_bf16 v[122:125], v[162:165], v[186:189], v[122:125]
	v_mfma_f32_16x16x32_bf16 v[110:113], v[154:157], v[194:197], v[110:113]
	v_mfma_f32_16x16x32_bf16 v[106:109], v[162:165], v[194:197], v[106:109]
	v_mfma_f32_16x16x32_bf16 v[94:97], v[154:157], v[230:233], v[94:97]
	v_mfma_f32_16x16x32_bf16 v[90:93], v[162:165], v[230:233], v[90:93]
	v_mfma_f32_16x16x32_bf16 v[78:81], v[154:157], v[238:241], v[78:81]
	v_mfma_f32_16x16x32_bf16 v[74:77], v[162:165], v[238:241], v[74:77]
	v_mfma_f32_16x16x32_bf16 v[118:121], v[166:169], v[182:185], v[118:121]
	v_mfma_f32_16x16x32_bf16 v[114:117], v[174:177], v[182:185], v[114:117]
	v_mfma_f32_16x16x32_bf16 v[102:105], v[166:169], v[190:193], v[102:105]
	v_mfma_f32_16x16x32_bf16 v[98:101], v[174:177], v[190:193], v[98:101]
	v_mfma_f32_16x16x32_bf16 v[86:89], v[166:169], v[198:201], v[86:89]
	v_mfma_f32_16x16x32_bf16 v[82:85], v[174:177], v[198:201], v[82:85]
	v_mfma_f32_16x16x32_bf16 v[70:73], v[166:169], v[234:237], v[70:73]
	v_mfma_f32_16x16x32_bf16 v[66:69], v[174:177], v[234:237], v[66:69]
	v_mfma_f32_16x16x32_bf16 v[118:121], v[170:173], v[186:189], v[118:121]
	v_mfma_f32_16x16x32_bf16 v[114:117], v[178:181], v[186:189], v[114:117]
	v_mfma_f32_16x16x32_bf16 v[102:105], v[170:173], v[194:197], v[102:105]
	v_mfma_f32_16x16x32_bf16 v[98:101], v[178:181], v[194:197], v[98:101]
	v_mfma_f32_16x16x32_bf16 v[86:89], v[170:173], v[230:233], v[86:89]
	v_mfma_f32_16x16x32_bf16 v[82:85], v[178:181], v[230:233], v[82:85]
	v_mfma_f32_16x16x32_bf16 v[70:73], v[170:173], v[238:241], v[70:73]
	v_mfma_f32_16x16x32_bf16 v[66:69], v[178:181], v[238:241], v[66:69]
	s_setprio 0
	s_barrier
	s_add_i32 s22, s88, s48
	v_lshl_add_u64 v[206:207], s[38:39], 0, v[202:203]
	s_mov_b32 m0, s22
	ds_read_b128 v[182:185], v149 offset:16384
	ds_read_b128 v[186:189], v149 offset:17408
	ds_read_b128 v[190:193], v149 offset:18432
	ds_read_b128 v[194:197], v149 offset:19456
	ds_read_b128 v[198:201], v149 offset:20480
	ds_read_b128 v[230:233], v149 offset:21504
	ds_read_b128 v[234:237], v149 offset:22528
	ds_read_b128 v[238:241], v149 offset:23552
	global_load_lds_dwordx4 v[206:207], off
	s_add_i32 m0, s22, 0x2000
	s_add_u32 s88, s38, 0x160000
	v_lshl_add_u64 v[242:243], s[38:39], 0, v[134:135]
	s_addc_u32 s89, s39, 0
	s_add_i32 s1, s1, s48
	global_load_lds_dwordx4 v[242:243], off
	v_lshl_add_u64 v[244:245], s[88:89], 0, v[202:203]
	s_mov_b32 m0, s1
	v_lshl_add_u64 v[246:247], s[2:3], 0, v[132:133]
	global_load_lds_dwordx4 v[244:245], off
	v_lshl_add_u64 v[244:245], s[88:89], 0, v[134:135]
	s_add_i32 m0, s1, 0x2000
	s_nop 0
	global_load_lds_dwordx4 v[244:245], off
	v_lshl_add_u64 v[244:245], s[2:3], 0, v[130:131]
	s_mov_b32 m0, s62
	s_nop 0
	global_load_lds_dwordx4 v[244:245], off
	s_mov_b32 m0, s63
	s_nop 0
	global_load_lds_dwordx4 v[246:247], off
	s_waitcnt vmcnt(8)
	s_waitcnt lgkmcnt(0)
	s_barrier
	s_setprio 1
	v_mfma_f32_16x16x32_bf16 v[62:65], v[150:153], v[182:185], v[62:65]
	v_mfma_f32_16x16x32_bf16 v[58:61], v[158:161], v[182:185], v[58:61]
	v_mfma_f32_16x16x32_bf16 v[46:49], v[150:153], v[190:193], v[46:49]
	v_mfma_f32_16x16x32_bf16 v[42:45], v[158:161], v[190:193], v[42:45]
	v_mfma_f32_16x16x32_bf16 v[30:33], v[150:153], v[198:201], v[30:33]
	v_mfma_f32_16x16x32_bf16 v[26:29], v[158:161], v[198:201], v[26:29]
	v_mfma_f32_16x16x32_bf16 v[14:17], v[150:153], v[234:237], v[14:17]
	v_mfma_f32_16x16x32_bf16 v[10:13], v[158:161], v[234:237], v[10:13]
	v_mfma_f32_16x16x32_bf16 v[62:65], v[154:157], v[186:189], v[62:65]
	v_mfma_f32_16x16x32_bf16 v[58:61], v[162:165], v[186:189], v[58:61]
	v_mfma_f32_16x16x32_bf16 v[46:49], v[154:157], v[194:197], v[46:49]
	v_mfma_f32_16x16x32_bf16 v[42:45], v[162:165], v[194:197], v[42:45]
	v_mfma_f32_16x16x32_bf16 v[30:33], v[154:157], v[230:233], v[30:33]
	v_mfma_f32_16x16x32_bf16 v[26:29], v[162:165], v[230:233], v[26:29]
	v_mfma_f32_16x16x32_bf16 v[14:17], v[154:157], v[238:241], v[14:17]
	v_mfma_f32_16x16x32_bf16 v[10:13], v[162:165], v[238:241], v[10:13]
	v_mfma_f32_16x16x32_bf16 v[54:57], v[166:169], v[182:185], v[54:57]
	v_mfma_f32_16x16x32_bf16 v[50:53], v[174:177], v[182:185], v[50:53]
	v_mfma_f32_16x16x32_bf16 v[38:41], v[166:169], v[190:193], v[38:41]
	v_mfma_f32_16x16x32_bf16 v[34:37], v[174:177], v[190:193], v[34:37]
	v_mfma_f32_16x16x32_bf16 v[22:25], v[166:169], v[198:201], v[22:25]
	v_mfma_f32_16x16x32_bf16 v[18:21], v[174:177], v[198:201], v[18:21]
	v_mfma_f32_16x16x32_bf16 v[6:9], v[166:169], v[234:237], v[6:9]
	v_mfma_f32_16x16x32_bf16 v[2:5], v[174:177], v[234:237], v[2:5]
	v_mfma_f32_16x16x32_bf16 v[54:57], v[170:173], v[186:189], v[54:57]
	v_mfma_f32_16x16x32_bf16 v[50:53], v[178:181], v[186:189], v[50:53]
	v_mfma_f32_16x16x32_bf16 v[38:41], v[170:173], v[194:197], v[38:41]
	v_mfma_f32_16x16x32_bf16 v[34:37], v[178:181], v[194:197], v[34:37]
	v_mfma_f32_16x16x32_bf16 v[22:25], v[170:173], v[230:233], v[22:25]
	v_mfma_f32_16x16x32_bf16 v[18:21], v[178:181], v[230:233], v[18:21]
	v_mfma_f32_16x16x32_bf16 v[6:9], v[170:173], v[238:241], v[6:9]
	v_mfma_f32_16x16x32_bf16 v[2:5], v[178:181], v[238:241], v[2:5]
	s_setprio 0
	s_barrier
	s_add_i32 s1, 0, 0x18000
	s_add_i32 s22, 0, 0x1c000
	v_add_u32_e32 v162, s1, v146
	v_add_u32_e32 v178, s22, v146
	ds_read_b128 v[150:153], v162
	ds_read_b128 v[154:157], v162 offset:1024
	ds_read_b128 v[158:161], v162 offset:2048
	ds_read_b128 v[162:165], v162 offset:3072
	ds_read_b128 v[166:169], v178
	ds_read_b128 v[170:173], v178 offset:1024
	ds_read_b128 v[174:177], v178 offset:2048
	ds_read_b128 v[178:181], v178 offset:3072
	s_add_u32 s2, s2, 0x160000
	s_addc_u32 s3, s3, 0
	s_mov_b32 m0, s68
	v_lshl_add_u64 v[248:249], s[2:3], 0, v[130:131]
	ds_read_b128 v[182:185], v149 offset:32768
	ds_read_b128 v[186:189], v149 offset:33792
	ds_read_b128 v[190:193], v149 offset:34816
	ds_read_b128 v[194:197], v149 offset:35840
	ds_read_b128 v[198:201], v149 offset:36864
	ds_read_b128 v[230:233], v149 offset:37888
	ds_read_b128 v[234:237], v149 offset:38912
	ds_read_b128 v[238:241], v149 offset:39936
	global_load_lds_dwordx4 v[248:249], off
	v_lshl_add_u64 v[248:249], s[2:3], 0, v[132:133]
	s_mov_b32 m0, s69
	s_nop 0
	global_load_lds_dwordx4 v[248:249], off
	s_waitcnt vmcnt(8)
	s_waitcnt lgkmcnt(0)
	s_barrier
	s_setprio 1
	v_mfma_f32_16x16x32_bf16 v[126:129], v[150:153], v[182:185], v[126:129]
	v_mfma_f32_16x16x32_bf16 v[122:125], v[158:161], v[182:185], v[122:125]
	v_mfma_f32_16x16x32_bf16 v[110:113], v[150:153], v[190:193], v[110:113]
	v_mfma_f32_16x16x32_bf16 v[106:109], v[158:161], v[190:193], v[106:109]
	v_mfma_f32_16x16x32_bf16 v[94:97], v[150:153], v[198:201], v[94:97]
	v_mfma_f32_16x16x32_bf16 v[90:93], v[158:161], v[198:201], v[90:93]
	v_mfma_f32_16x16x32_bf16 v[78:81], v[150:153], v[234:237], v[78:81]
	v_mfma_f32_16x16x32_bf16 v[74:77], v[158:161], v[234:237], v[74:77]
	v_mfma_f32_16x16x32_bf16 v[126:129], v[154:157], v[186:189], v[126:129]
	v_mfma_f32_16x16x32_bf16 v[122:125], v[162:165], v[186:189], v[122:125]
	v_mfma_f32_16x16x32_bf16 v[110:113], v[154:157], v[194:197], v[110:113]
	v_mfma_f32_16x16x32_bf16 v[106:109], v[162:165], v[194:197], v[106:109]
	v_mfma_f32_16x16x32_bf16 v[94:97], v[154:157], v[230:233], v[94:97]
	v_mfma_f32_16x16x32_bf16 v[90:93], v[162:165], v[230:233], v[90:93]
	v_mfma_f32_16x16x32_bf16 v[78:81], v[154:157], v[238:241], v[78:81]
	v_mfma_f32_16x16x32_bf16 v[74:77], v[162:165], v[238:241], v[74:77]
	v_mfma_f32_16x16x32_bf16 v[118:121], v[166:169], v[182:185], v[118:121]
	v_mfma_f32_16x16x32_bf16 v[114:117], v[174:177], v[182:185], v[114:117]
	v_mfma_f32_16x16x32_bf16 v[102:105], v[166:169], v[190:193], v[102:105]
	v_mfma_f32_16x16x32_bf16 v[98:101], v[174:177], v[190:193], v[98:101]
	v_mfma_f32_16x16x32_bf16 v[86:89], v[166:169], v[198:201], v[86:89]
	v_mfma_f32_16x16x32_bf16 v[82:85], v[174:177], v[198:201], v[82:85]
	v_mfma_f32_16x16x32_bf16 v[70:73], v[166:169], v[234:237], v[70:73]
	v_mfma_f32_16x16x32_bf16 v[66:69], v[174:177], v[234:237], v[66:69]
	v_mfma_f32_16x16x32_bf16 v[118:121], v[170:173], v[186:189], v[118:121]
	v_mfma_f32_16x16x32_bf16 v[114:117], v[178:181], v[186:189], v[114:117]
	v_mfma_f32_16x16x32_bf16 v[102:105], v[170:173], v[194:197], v[102:105]
	v_mfma_f32_16x16x32_bf16 v[98:101], v[178:181], v[194:197], v[98:101]
	v_mfma_f32_16x16x32_bf16 v[86:89], v[170:173], v[230:233], v[86:89]
	v_mfma_f32_16x16x32_bf16 v[82:85], v[178:181], v[230:233], v[82:85]
	v_mfma_f32_16x16x32_bf16 v[70:73], v[170:173], v[238:241], v[70:73]
	v_mfma_f32_16x16x32_bf16 v[66:69], v[178:181], v[238:241], v[66:69]
	s_setprio 0
	s_barrier
	s_add_i32 s1, s1, s48
	v_lshl_add_u64 v[206:207], v[206:207], 0, s[42:43]
	s_mov_b32 m0, s1
	ds_read_b128 v[182:185], v149 offset:49152
	ds_read_b128 v[186:189], v149 offset:50176
	ds_read_b128 v[190:193], v149 offset:51200
	ds_read_b128 v[194:197], v149 offset:52224
	ds_read_b128 v[198:201], v149 offset:53248
	ds_read_b128 v[230:233], v149 offset:54272
	ds_read_b128 v[234:237], v149 offset:55296
	ds_read_b128 v[238:241], v149 offset:56320
	global_load_lds_dwordx4 v[206:207], off
	s_add_i32 m0, s1, 0x2000
	s_add_u32 s2, s38, 0x160080
	v_lshl_add_u64 v[206:207], v[242:243], 0, s[42:43]
	s_addc_u32 s3, s39, 0
	s_add_i32 s1, s22, s48
	global_load_lds_dwordx4 v[206:207], off
	v_lshl_add_u64 v[206:207], s[2:3], 0, v[202:203]
	s_mov_b32 m0, s1
	s_nop 0
	global_load_lds_dwordx4 v[206:207], off
	v_lshl_add_u64 v[206:207], s[2:3], 0, v[134:135]
	s_add_i32 m0, s1, 0x2000
	s_nop 0
	global_load_lds_dwordx4 v[206:207], off
	v_lshl_add_u64 v[206:207], v[244:245], 0, s[42:43]
	s_mov_b32 m0, s81
	s_nop 0
	global_load_lds_dwordx4 v[206:207], off
	v_lshl_add_u64 v[206:207], v[246:247], 0, s[42:43]
	s_mov_b32 m0, s82
	s_nop 0
	global_load_lds_dwordx4 v[206:207], off
	s_waitcnt vmcnt(8)
	s_waitcnt lgkmcnt(0)
	s_barrier
	s_setprio 1
	v_mfma_f32_16x16x32_bf16 v[62:65], v[150:153], v[182:185], v[62:65]
	v_mfma_f32_16x16x32_bf16 v[58:61], v[158:161], v[182:185], v[58:61]
	v_mfma_f32_16x16x32_bf16 v[46:49], v[150:153], v[190:193], v[46:49]
	v_mfma_f32_16x16x32_bf16 v[42:45], v[158:161], v[190:193], v[42:45]
	v_mfma_f32_16x16x32_bf16 v[30:33], v[150:153], v[198:201], v[30:33]
	v_mfma_f32_16x16x32_bf16 v[26:29], v[158:161], v[198:201], v[26:29]
	v_mfma_f32_16x16x32_bf16 v[14:17], v[150:153], v[234:237], v[14:17]
	v_mfma_f32_16x16x32_bf16 v[10:13], v[158:161], v[234:237], v[10:13]
	v_mfma_f32_16x16x32_bf16 v[62:65], v[154:157], v[186:189], v[62:65]
	v_mfma_f32_16x16x32_bf16 v[58:61], v[162:165], v[186:189], v[58:61]
	v_mfma_f32_16x16x32_bf16 v[46:49], v[154:157], v[194:197], v[46:49]
	v_mfma_f32_16x16x32_bf16 v[42:45], v[162:165], v[194:197], v[42:45]
	v_mfma_f32_16x16x32_bf16 v[30:33], v[154:157], v[230:233], v[30:33]
	v_mfma_f32_16x16x32_bf16 v[26:29], v[162:165], v[230:233], v[26:29]
	v_mfma_f32_16x16x32_bf16 v[14:17], v[154:157], v[238:241], v[14:17]
	v_mfma_f32_16x16x32_bf16 v[10:13], v[162:165], v[238:241], v[10:13]
	v_mfma_f32_16x16x32_bf16 v[54:57], v[166:169], v[182:185], v[54:57]
	v_mfma_f32_16x16x32_bf16 v[50:53], v[174:177], v[182:185], v[50:53]
	v_mfma_f32_16x16x32_bf16 v[38:41], v[166:169], v[190:193], v[38:41]
	v_mfma_f32_16x16x32_bf16 v[34:37], v[174:177], v[190:193], v[34:37]
	v_mfma_f32_16x16x32_bf16 v[22:25], v[166:169], v[198:201], v[22:25]
	v_mfma_f32_16x16x32_bf16 v[18:21], v[174:177], v[198:201], v[18:21]
	v_mfma_f32_16x16x32_bf16 v[6:9], v[166:169], v[234:237], v[6:9]
	v_mfma_f32_16x16x32_bf16 v[2:5], v[174:177], v[234:237], v[2:5]
	v_mfma_f32_16x16x32_bf16 v[54:57], v[170:173], v[186:189], v[54:57]
	v_mfma_f32_16x16x32_bf16 v[50:53], v[178:181], v[186:189], v[50:53]
	v_mfma_f32_16x16x32_bf16 v[38:41], v[170:173], v[194:197], v[38:41]
	v_mfma_f32_16x16x32_bf16 v[34:37], v[178:181], v[194:197], v[34:37]
	v_mfma_f32_16x16x32_bf16 v[22:25], v[170:173], v[230:233], v[22:25]
	v_mfma_f32_16x16x32_bf16 v[18:21], v[178:181], v[230:233], v[18:21]
	v_mfma_f32_16x16x32_bf16 v[6:9], v[170:173], v[238:241], v[6:9]
	v_mfma_f32_16x16x32_bf16 v[2:5], v[178:181], v[238:241], v[2:5]
	s_setprio 0
	s_barrier
	s_add_i32 s1, s0, 2
	s_add_u32 s28, s28, 0x100
	s_addc_u32 s29, s29, 0
	v_lshl_add_u64 v[142:143], v[142:143], 0, s[70:71]
	v_lshl_add_u64 v[140:141], v[140:141], 0, s[70:71]
	s_cmp_ge_i32 s0, s91
	s_mov_b32 s0, s1
	s_cbranch_scc0 .LBB0_1247
	s_and_b64 vcc, exec, s[34:35]
	s_cbranch_vccz .LBB0_1250
	s_barrier
